# phase_prep part 3 (transposed conv): main, halo (unconditional, selected afterwards) and weight loads of an iteration issued together, one wait (were five)
# speedup vs baseline: 1.0022x; 1.0022x over previous
.LBB0_417:
	v_mov_b32_e32 v0, v108
	v_mov_b32_e32 v10, v109
	v_mov_b32_e32 v12, v110
	v_mov_b32_e32 v16, v111
	v_mov_b32_e32 v18, v112
	v_mov_b32_e32 v20, v113
	s_movk_i32 s0, 0x2000
	s_nop 0
	v_lshlrev_b32_e32 v32, 16, v8
	s_nop 0
	v_and_b32_e32 v33, 0xffff0000, v8
	v_and_b32_e32 v8, 0xffff0000, v4
	v_lshlrev_b32_e32 v36, 16, v6
	v_and_b32_e32 v37, 0xffff0000, v6
	v_lshlrev_b32_e32 v30, 16, v7
	v_and_b32_e32 v31, 0xffff0000, v7
	v_lshlrev_b32_e32 v28, 16, v9
	v_and_b32_e32 v29, 0xffff0000, v9
	v_and_b32_e32 v9, 16, v5
	v_lshlrev_b32_e32 v7, 16, v5
	v_mov_b32_e32 v6, v8
	v_pk_mov_b32 v[34:35], v[6:7], v[8:9] op_sel:[1,0]
	v_lshlrev_b32_e32 v24, 16, v2
	v_and_b32_e32 v25, 0xffff0000, v2
	v_lshlrev_b32_e32 v22, 16, v3
	v_and_b32_e32 v23, 0xffff0000, v3
	v_lshlrev_b32_e32 v2, 16, v4
	v_pk_mov_b32 v[38:39], v[26:27], v[36:37] op_sel:[1,0]
	v_pk_mov_b32 v[40:41], v[36:37], v[30:31] op_sel:[1,0]
	v_mov_b32_e32 v3, v35
	v_and_b32_e32 v35, 0xffff0000, v5
	v_pk_mov_b32 v[42:43], v[30:31], v[32:33] op_sel:[1,0]
	v_pk_mov_b32 v[44:45], v[32:33], v[28:29] op_sel:[1,0]
	v_pk_mov_b32 v[46:47], v[28:29], v[24:25] op_sel:[1,0]
	v_mul_hi_u32_u24_e32 v15, 0x9000, v19
	v_mul_u32_u24_e32 v14, 0x9000, v19
	v_lshl_add_u64 v[62:63], v[62:63], 0, s[60:61]
	s_mov_b64 s[0:1], 0x8ffff
	v_cmp_lt_u64_e32 vcc, s[0:1], v[62:63]
	s_or_b64 s[24:25], vcc, s[24:25]
	v_pk_fma_f32 v[4:5], v[26:27], v[10:11], v[0:1] op_sel_hi:[1,0,0]
	v_pk_fma_f32 v[26:27], v[10:11], v[36:37], v[0:1] op_sel_hi:[0,1,0]
	v_pk_fma_f32 v[48:49], v[10:11], v[30:31], v[0:1] op_sel_hi:[0,1,0]
	v_pk_fma_f32 v[50:51], v[10:11], v[32:33], v[0:1] op_sel_hi:[0,1,0]
	v_pk_fma_f32 v[26:27], v[12:13], v[40:41], v[26:27] op_sel_hi:[0,1,1]
	v_pk_fma_f32 v[4:5], v[38:39], v[12:13], v[4:5] op_sel_hi:[1,0,1]
	v_pk_fma_f32 v[38:39], v[12:13], v[42:43], v[48:49] op_sel_hi:[0,1,1]
	v_pk_fma_f32 v[48:49], v[12:13], v[44:45], v[50:51] op_sel_hi:[0,1,1]
	v_pk_fma_f32 v[26:27], v[16:17], v[30:31], v[26:27] op_sel_hi:[0,1,1]
	v_pk_fma_f32 v[4:5], v[16:17], v[36:37], v[4:5] op_sel_hi:[0,1,1]
	v_pk_fma_f32 v[36:37], v[16:17], v[32:33], v[38:39] op_sel_hi:[0,1,1]
	v_pk_fma_f32 v[38:39], v[16:17], v[28:29], v[48:49] op_sel_hi:[0,1,1]
	v_pk_fma_f32 v[26:27], v[18:19], v[42:43], v[26:27] op_sel_hi:[0,1,1]
	v_pk_fma_f32 v[4:5], v[18:19], v[40:41], v[4:5] op_sel_hi:[0,1,1]
	v_pk_fma_f32 v[36:37], v[18:19], v[44:45], v[36:37] op_sel_hi:[0,1,1]
	v_pk_fma_f32 v[38:39], v[18:19], v[46:47], v[38:39] op_sel_hi:[0,1,1]
	v_pk_fma_f32 v[26:27], v[20:21], v[32:33], v[26:27] op_sel_hi:[0,1,1]
	v_pk_fma_f32 v[4:5], v[20:21], v[30:31], v[4:5] op_sel_hi:[0,1,1]
	v_pk_fma_f32 v[30:31], v[20:21], v[28:29], v[36:37] op_sel_hi:[0,1,1]
	v_pk_fma_f32 v[32:33], v[20:21], v[24:25], v[38:39] op_sel_hi:[0,1,1]
	v_mul_f32_e32 v21, 0xbfb8aa3b, v26
	v_mul_f32_e32 v36, 0xbfb8aa3b, v27
	v_mul_f32_e32 v38, 0xbfb8aa3b, v31
	v_exp_f32_e32 v21, v21
	v_exp_f32_e32 v36, v36
	v_exp_f32_e32 v38, v38
	v_mul_f32_e32 v9, 0xbfb8aa3b, v4
	v_mul_f32_e32 v19, 0xbfb8aa3b, v5
	v_mul_f32_e32 v37, 0xbfb8aa3b, v30
	v_mul_f32_e32 v39, 0xbfb8aa3b, v32
	v_exp_f32_e32 v9, v9
	v_exp_f32_e32 v19, v19
	v_exp_f32_e32 v37, v37
	v_exp_f32_e32 v43, v39
	v_add_f32_e32 v21, 1.0, v21
	v_add_f32_e32 v39, 1.0, v36
	v_add_f32_e32 v41, 1.0, v38
	v_rcp_f32_e32 v38, v21
	v_rcp_f32_e32 v39, v39
	v_mul_f32_e32 v42, 0xbfb8aa3b, v33
	v_add_f32_e32 v9, 1.0, v9
	v_add_f32_e32 v19, 1.0, v19
	v_pk_fma_f32 v[28:29], v[10:11], v[28:29], v[0:1] op_sel_hi:[0,1,0]
	v_add_f32_e32 v40, 1.0, v37
	v_rcp_f32_e32 v36, v9
	v_rcp_f32_e32 v37, v19
	v_exp_f32_e32 v9, v42
	v_pk_fma_f32 v[28:29], v[12:13], v[46:47], v[28:29] op_sel_hi:[0,1,1]
	v_pk_mul_f32 v[26:27], v[26:27], v[38:39]
	v_add_f32_e32 v19, 1.0, v43
	v_pk_fma_f32 v[28:29], v[16:17], v[24:25], v[28:29] op_sel_hi:[0,1,1]
	v_pk_mov_b32 v[38:39], v[24:25], v[22:23] op_sel:[1,0]
	v_pk_mul_f32 v[4:5], v[4:5], v[36:37]
	v_pk_fma_f32 v[28:29], v[18:19], v[38:39], v[28:29] op_sel_hi:[0,1,1]
	v_pk_fma_f32 v[28:29], v[20:21], v[22:23], v[28:29] op_sel_hi:[0,1,1]
	v_rcp_f32_e32 v36, v19
	v_add_f32_e32 v9, 1.0, v9
	v_mul_f32_e32 v19, 0xbfb8aa3b, v29
	v_rcp_f32_e32 v40, v40
	v_rcp_f32_e32 v41, v41
	v_rcp_f32_e32 v37, v9
	v_mul_f32_e32 v9, 0xbfb8aa3b, v28
	v_exp_f32_e32 v19, v19
	v_exp_f32_e32 v9, v9
	v_pk_fma_f32 v[24:25], v[10:11], v[24:25], v[0:1] op_sel_hi:[0,1,0]
	v_pk_fma_f32 v[24:25], v[12:13], v[38:39], v[24:25] op_sel_hi:[0,1,1]
	v_pk_fma_f32 v[24:25], v[16:17], v[22:23], v[24:25] op_sel_hi:[0,1,1]
	v_pk_mov_b32 v[38:39], v[22:23], v[2:3] op_sel:[1,0]
	v_pk_mul_f32 v[30:31], v[30:31], v[40:41]
	v_pk_fma_f32 v[24:25], v[18:19], v[38:39], v[24:25] op_sel_hi:[0,1,1]
	v_mov_b32_e32 v40, v2
	v_mov_b32_e32 v41, v8
	v_add_f32_e32 v9, 1.0, v9
	v_pk_fma_f32 v[24:25], v[20:21], v[40:41], v[24:25] op_sel_hi:[0,1,1]
	v_pk_mul_f32 v[32:33], v[32:33], v[36:37]
	v_rcp_f32_e32 v36, v9
	v_add_f32_e32 v9, 1.0, v19
	v_mul_f32_e32 v19, 0xbfb8aa3b, v24
	v_exp_f32_e32 v19, v19
	v_mul_f32_e32 v21, 0xbfb8aa3b, v25
	v_exp_f32_e32 v21, v21
	v_pk_fma_f32 v[22:23], v[10:11], v[22:23], v[0:1] op_sel_hi:[0,1,0]
	v_rcp_f32_e32 v37, v9
	v_add_f32_e32 v9, 1.0, v19
	v_pk_fma_f32 v[22:23], v[12:13], v[38:39], v[22:23] op_sel_hi:[0,1,1]
	v_rcp_f32_e32 v42, v9
	v_add_f32_e32 v19, 1.0, v21
	v_pk_fma_f32 v[22:23], v[16:17], v[40:41], v[22:23] op_sel_hi:[0,1,1]
	v_mov_b32_e32 v9, v34
	v_pk_fma_f32 v[8:9], v[18:19], v[8:9], v[22:23] op_sel_hi:[0,1,1]
	v_pk_fma_f32 v[8:9], v[20:21], v[34:35], v[8:9] op_sel_hi:[0,1,1]
	v_mul_f32_e32 v21, 0xbfb8aa3b, v8
	v_exp_f32_e32 v21, v21
	v_mul_f32_e32 v22, 0xbfb8aa3b, v9
	v_exp_f32_e32 v23, v22
	v_pk_fma_f32 v[2:3], v[10:11], v[2:3], v[0:1] op_sel_hi:[0,1,0]
	v_rcp_f32_e32 v43, v19
	v_add_f32_e32 v19, 1.0, v21
	v_pk_fma_f32 v[2:3], v[12:13], v[6:7], v[2:3] op_sel_hi:[0,1,1]
	v_rcp_f32_e32 v22, v19
	v_add_f32_e32 v19, 1.0, v23
	v_pk_fma_f32 v[2:3], v[16:17], v[34:35], v[2:3] op_sel_hi:[0,1,1]
	v_mov_b32_e32 v10, v35
	v_pk_fma_f32 v[2:3], v[18:19], v[10:11], v[2:3] op_sel_hi:[0,1,1]
	v_mov_b32_e32 v12, v11
	v_pk_fma_f32 v[2:3], v[12:13], v[20:21], v[2:3] op_sel_hi:[1,0,1]
	v_rcp_f32_e32 v23, v19
	v_mul_f32_e32 v0, 0xbfb8aa3b, v2
	v_exp_f32_e32 v0, v0
	v_mul_f32_e32 v6, 0xbfb8aa3b, v3
	v_exp_f32_e32 v7, v6
	v_pk_mul_f32 v[10:11], v[28:29], v[36:37]
	v_add_f32_e32 v0, 1.0, v0
	v_rcp_f32_e32 v6, v0
	v_add_f32_e32 v0, 1.0, v7
	v_rcp_f32_e32 v7, v0
	v_pk_mul_f32 v[12:13], v[24:25], v[42:43]
	v_pk_mul_f32 v[8:9], v[8:9], v[22:23]
	v_lshlrev_b32_e32 v0, 1, v17
	v_pk_mul_f32 v[18:19], v[2:3], v[6:7]
	v_cvt_pk_bf16_f32 v6, v10, v11
	v_lshl_add_u64 v[10:11], s[8:9], 0, v[14:15]
	v_cvt_pk_bf16_f32 v2, v4, v5
	v_cvt_pk_bf16_f32 v3, v26, v27
	v_cvt_pk_bf16_f32 v4, v30, v31
	v_cvt_pk_bf16_f32 v5, v32, v33
	v_cvt_pk_bf16_f32 v7, v12, v13
	v_cvt_pk_bf16_f32 v8, v8, v9
	v_cvt_pk_bf16_f32 v9, v18, v19
	v_lshl_add_u64 v[10:11], v[10:11], 0, v[0:1]
	global_store_dwordx4 v[10:11], v[2:5], off
	global_store_dwordx4 v[10:11], v[6:9], off offset:16
	s_andn2_b64 exec, exec, s[24:25]
	s_cbranch_execz .LBB0_424
.LBB0_418:
	s_mov_b32 s0, 0x38e38e39
	v_mul_hi_u32 v0, v62, s0
	v_lshrrev_b32_e32 v19, 8, v0
	v_mul_u32_u24_e32 v0, 0x480, v19
	v_sub_u32_e32 v10, v62, v0
	v_mov_b64_e32 v[2:3], s[22:23]
	s_mov_b32 s0, 0x9000
	v_mad_u64_u32 v[2:3], s[0:1], v19, s0, v[2:3]
	v_lshlrev_b32_e32 v0, 5, v10
	v_lshl_add_u64 v[14:15], v[2:3], 0, v[0:1]
	global_load_dwordx4 v[6:9], v[14:15], off
	global_load_dwordx4 v[2:5], v[14:15], off offset:16
	v_add_co_u32_e64 v12, s[96:97], -4, v14
	s_nop 1
	v_addc_co_u32_e64 v13, s[96:97], -1, v15, s[96:97]
	global_load_dword v100, v[12:13], off
	global_load_ushort v101, v[14:15], off offset:32
	global_load_ushort v102, v[14:15], off offset:34
	v_lshlrev_b32_e32 v104, 2, v19
	v_mov_b32_e32 v105, 0
	v_lshl_add_u64 v[106:107], s[14:15], 0, v[104:105]
	v_lshl_add_u64 v[104:105], s[12:13], 0, v[104:105]
	global_load_dword v108, v[106:107], off
	global_load_dword v109, v[104:105], off
	global_load_dword v110, v[104:105], off offset:3072
	v_add_co_u32_e32 v106, vcc, s83, v104
	s_nop 1
	v_addc_co_u32_e32 v107, vcc, 0, v105, vcc
	global_load_dword v111, v[106:107], off offset:2048
	v_add_co_u32_e32 v106, vcc, 0x2000, v104
	s_nop 1
	v_addc_co_u32_e32 v107, vcc, 0, v105, vcc
	global_load_dword v112, v[106:107], off offset:1024
	v_add_co_u32_e32 v106, vcc, s2, v104
	s_nop 1
	v_addc_co_u32_e32 v107, vcc, 0, v105, vcc
	global_load_dword v113, v[106:107], off
	s_movk_i32 s0, 0x400
	v_mov_b32_e32 v0, 0xf0
	v_mov_b32_e32 v11, 0x7f0
	v_cmp_gt_u32_e32 vcc, s0, v10
	v_lshlrev_b32_e32 v17, 4, v10
	v_mov_b32_e32 v26, 0
	v_cndmask_b32_e32 v0, v0, v11, vcc
	v_and_b32_e32 v0, v0, v17
	v_cmp_ne_u32_e64 s[38:39], 0, v0
	v_mov_b32_e32 v11, 0
	v_mov_b32_e32 v27, 0
	s_waitcnt vmcnt(0) lgkmcnt(0)
	v_lshlrev_b32_e32 v26, 16, v100
	v_and_b32_e32 v27, 0xffff0000, v100
	v_cndmask_b32_e64 v26, 0, v26, s[38:39]
	v_cndmask_b32_e64 v27, 0, v27, s[38:39]
	v_mov_b32_e32 v10, 0x100
	v_cndmask_b32_e32 v10, v10, v163, vcc
	v_add_u32_e32 v12, 16, v0
	v_cmp_lt_u32_e32 vcc, v12, v10
	v_lshlrev_b32_e32 v11, 16, v101
	v_cndmask_b32_e32 v11, 0, v11, vcc
	v_add_u32_e32 v0, 17, v0
	v_cmp_lt_u32_e32 vcc, v0, v10
	v_lshlrev_b32_e32 v13, 16, v102
	v_cndmask_b32_e32 v13, 0, v13, vcc
	s_branch .LBB0_417
